# P0 x-RMSNorm loop unrolled by two register sets with the next row's loads prefetched
# baseline (speedup 1.0000x reference)
; DI unsigned pk2(float lo, float hi) { const f32x2 v = {lo, hi}; const hwbf16x2 b = __builtin_convertvector(v, hwbf16x2); return __builtin_bit_cast(unsigned, b); }
; DI float frcp(float x) { return __builtin_amdgcn_rcpf(x); }
; DI float frsq(float x) { return __builtin_amdgcn_rsqf(x); }
; DI void norm_row_bf16(const float* xrow, const float* g, bf16_t* orow, int lane, float* xs_out = nullptr) {
;     const f32x4* xr = (const f32x4*)xrow + lane; f32x4 v[8]; float s = 0.f;
; #pragma unroll
;     for (int j = 0; j < 8; ++j) { v[j] = xr[64 * j]; s += (v[j].x * v[j].x + v[j].y * v[j].y) + (v[j].z * v[j].z + v[j].w * v[j].w); }
;     s = wave_sum(s);
;     const float rs = frsq(s * (1.0f / DM) + 1e-6f);
;     if (xs_out && lane == 0) *xs_out = frcp(rs);
;     const f32x4* gr = (const f32x4*)g + lane;
;     u32x2* o8 = (u32x2*)orow + lane;
; #pragma unroll
;     for (int j = 0; j < 8; ++j) { const f32x4 gg = gr[64 * j]; u32x2 o; o.x = pk2(v[j].x * rs * gg.x, v[j].y * rs * gg.y); o.y = pk2(v[j].z * rs * gg.z, v[j].w * rs * gg.w); o8[64 * j] = o; }
; DI void prologue(const Params& p, LAS unsigned char* lds, int tid, int lane, int wave) {
;     ...
;     for (int m = gw; m < T_; m += NGW) norm_row_bf16(p.in[0] + (size_t)m * DM, p.in[1], HN + (size_t)m * DM, lane, XS + m);
.LBB0_111:
	s_cmpk_gt_i32 s6, 0x7fff
	v_mbcnt_lo_u32_b32 v169, -1, 0
	v_cmp_eq_u32_e32 vcc, 0, v1
	s_cbranch_scc1 .LBB0_116
	v_mbcnt_hi_u32_b32 v4, -1, v169
	v_and_b32_e32 v3, 64, v4
	v_add_u32_e32 v5, 64, v3
	v_xor_b32_e32 v3, 1, v4
	v_cmp_lt_i32_e64 s[0:1], v3, v5
	v_xor_b32_e32 v6, 2, v4
	v_lshlrev_b32_e32 v38, 4, v1
	v_cndmask_b32_e64 v3, v4, v3, s[0:1]
	v_cmp_lt_i32_e64 s[0:1], v6, v5
	v_mov_b32_e32 v39, 0
	v_lshl_add_u64 v[40:41], s[38:39], 0, v[38:39]
	v_cndmask_b32_e64 v6, v4, v6, s[0:1]
	v_lshlrev_b32_e32 v52, 2, v6
	v_xor_b32_e32 v6, 4, v4
	v_cmp_lt_i32_e64 s[0:1], v6, v5
	s_ashr_i32 s7, s6, 31
	s_mov_b64 s[8:9], 0x1000
	v_cndmask_b32_e64 v6, v4, v6, s[0:1]
	v_lshlrev_b32_e32 v53, 2, v6
	v_xor_b32_e32 v6, 8, v4
	v_cmp_lt_i32_e64 s[0:1], v6, v5
	v_lshl_add_u64 v[42:43], v[40:41], 0, s[8:9]
	v_mov_b32_e32 v37, v39
	v_cndmask_b32_e64 v6, v4, v6, s[0:1]
	v_lshlrev_b32_e32 v54, 2, v6
	v_xor_b32_e32 v6, 16, v4
	v_cmp_lt_i32_e64 s[0:1], v6, v5
	v_lshlrev_b32_e32 v3, 2, v3
	v_mov_b32_e32 v57, 0x358637bd
	v_cndmask_b32_e64 v6, v4, v6, s[0:1]
	v_lshlrev_b32_e32 v55, 2, v6
	v_xor_b32_e32 v6, 32, v4
	v_cmp_lt_i32_e64 s[0:1], v6, v5
	s_nop 1
	v_cndmask_b32_e64 v4, v4, v6, s[0:1]
	s_mov_b64 s[0:1], 0x1400
	v_lshl_add_u64 v[44:45], v[40:41], 0, s[0:1]
	s_mov_b64 s[0:1], 0x1800
	v_lshl_add_u64 v[46:47], v[40:41], 0, s[0:1]
	s_mov_b64 s[0:1], 0x1c00
	v_lshl_add_u64 v[48:49], v[40:41], 0, s[0:1]
	s_lshl_b64 s[0:1], s[6:7], 2
	s_add_u32 s0, s62, s0
	s_addc_u32 s1, s63, s1
	s_add_u32 s0, s0, 0x31b82000
	s_addc_u32 s1, s1, 0
	s_ashr_i32 s89, s88, 31
	s_lshl_b64 s[2:3], s[88:89], 2
	s_lshl_b64 s[10:11], s[6:7], 13
	s_add_u32 s10, s36, s10
	s_addc_u32 s11, s37, s11
	v_lshlrev_b32_e32 v56, 2, v4
	v_lshl_add_u64 v[4:5], s[10:11], 0, v[38:39]
	v_lshl_add_u64 v[50:51], v[4:5], 0, s[8:9]
	s_lshl_b64 s[8:9], s[88:89], 13
	s_lshl_b64 s[10:11], s[6:7], 12
	s_add_u32 s10, s62, s10
	s_addc_u32 s11, s63, s11
	v_lshl_add_u64 v[4:5], s[10:11], 0, v[36:37]
	s_mov_b64 s[10:11], 0x800
	v_lshl_add_u64 v[36:37], v[4:5], 0, s[10:11]
	s_lshl_b64 s[10:11], s[88:89], 12
	s_mov_b32 s7, s6
	global_load_dwordx4 v[80:83], v[40:41], off
	global_load_dwordx4 v[84:87], v[40:41], off offset:1024
	global_load_dwordx4 v[88:91], v[40:41], off offset:2048
	global_load_dwordx4 v[92:95], v[40:41], off offset:3072
	global_load_dwordx4 v[96:99], v[42:43], off
	global_load_dwordx4 v[100:103], v[44:45], off
	global_load_dwordx4 v[104:107], v[46:47], off
	global_load_dwordx4 v[108:111], v[48:49], off
	global_load_dwordx4 v[32:35], v[50:51], off offset:-4096
	global_load_dwordx4 v[28:31], v[50:51], off offset:-3072
	global_load_dwordx4 v[24:27], v[50:51], off offset:-2048
	global_load_dwordx4 v[20:23], v[50:51], off offset:-1024
	global_load_dwordx4 v[16:19], v[50:51], off
	global_load_dwordx4 v[12:15], v[50:51], off offset:1024
	global_load_dwordx4 v[8:11], v[50:51], off offset:2048
	global_load_dwordx4 v[4:7], v[50:51], off offset:3072
	s_waitcnt vmcnt(0)
	s_branch .LBB0_114

; DI unsigned pk2(float lo, float hi) { const f32x2 v = {lo, hi}; const hwbf16x2 b = __builtin_convertvector(v, hwbf16x2); return __builtin_bit_cast(unsigned, b); }
; DI float frcp(float x) { return __builtin_amdgcn_rcpf(x); }
; DI float frsq(float x) { return __builtin_amdgcn_rsqf(x); }
; DI void norm_row_bf16(const float* xrow, const float* g, bf16_t* orow, int lane, float* xs_out = nullptr) {
;     const f32x4* xr = (const f32x4*)xrow + lane; f32x4 v[8]; float s = 0.f;
; #pragma unroll
;     for (int j = 0; j < 8; ++j) { v[j] = xr[64 * j]; s += (v[j].x * v[j].x + v[j].y * v[j].y) + (v[j].z * v[j].z + v[j].w * v[j].w); }
;     s = wave_sum(s);
;     const float rs = frsq(s * (1.0f / DM) + 1e-6f);
;     if (xs_out && lane == 0) *xs_out = frcp(rs);
;     const f32x4* gr = (const f32x4*)g + lane;
;     u32x2* o8 = (u32x2*)orow + lane;
; #pragma unroll
;     for (int j = 0; j < 8; ++j) { const f32x4 gg = gr[64 * j]; u32x2 o; o.x = pk2(v[j].x * rs * gg.x, v[j].y * rs * gg.y); o.y = pk2(v[j].z * rs * gg.z, v[j].w * rs * gg.w); o8[64 * j] = o; }
.Lp0n_B:
	s_add_i32 s98, s7, s88
	s_cmpk_gt_i32 s98, 0x7fff
	s_cbranch_scc1 .Lp0n_nopfB
	v_lshl_add_u64 v[160:161], v[50:51], 0, s[8:9]
	global_load_dwordx4 v[32:35], v[160:161], off offset:-4096
	global_load_dwordx4 v[28:31], v[160:161], off offset:-3072
	global_load_dwordx4 v[24:27], v[160:161], off offset:-2048
	global_load_dwordx4 v[20:23], v[160:161], off offset:-1024
	global_load_dwordx4 v[16:19], v[160:161], off
	global_load_dwordx4 v[12:15], v[160:161], off offset:1024
	global_load_dwordx4 v[8:11], v[160:161], off offset:2048
	global_load_dwordx4 v[4:7], v[160:161], off offset:3072
	s_waitcnt vmcnt(17)
	s_branch .Lp0n_goB
.Lp0n_nopfB:
	s_waitcnt vmcnt(9)
.Lp0n_goB:
	v_mul_f32_e32 v38, v157, v157
	v_mul_f32_e32 v58, v159, v159
	v_mul_f32_e32 v59, v153, v153
	v_mul_f32_e32 v60, v155, v155
	v_mul_f32_e32 v61, v149, v149
	v_mul_f32_e32 v62, v151, v151
	v_fmac_f32_e32 v38, v156, v156
	v_fmac_f32_e32 v58, v158, v158
	v_fmac_f32_e32 v59, v152, v152
	v_fmac_f32_e32 v60, v154, v154
	v_mul_f32_e32 v63, v145, v145
	v_mul_f32_e32 v64, v147, v147
	v_fmac_f32_e32 v61, v148, v148
	v_fmac_f32_e32 v62, v150, v150
	v_add_f32_e32 v38, v38, v58
	v_add_f32_e32 v58, v59, v60
	v_mul_f32_e32 v65, v141, v141
	v_mul_f32_e32 v66, v143, v143
	v_fmac_f32_e32 v63, v144, v144
	v_fmac_f32_e32 v64, v146, v146
	v_add_f32_e32 v59, v61, v62
	v_add_f32_e32 v38, v38, v58
	v_mul_f32_e32 v67, v137, v137
	v_mul_f32_e32 v68, v139, v139
	v_fmac_f32_e32 v65, v140, v140
	v_fmac_f32_e32 v66, v142, v142
	v_add_f32_e32 v60, v63, v64
	v_add_f32_e32 v38, v38, v59
	v_mul_f32_e32 v69, v133, v133
	v_mul_f32_e32 v70, v135, v135
	v_fmac_f32_e32 v67, v136, v136
	v_fmac_f32_e32 v68, v138, v138
	v_add_f32_e32 v61, v65, v66
	v_add_f32_e32 v38, v38, v60
	v_mul_f32_e32 v71, v129, v129
	v_mul_f32_e32 v72, v131, v131
	v_fmac_f32_e32 v69, v132, v132
	v_fmac_f32_e32 v70, v134, v134
	v_add_f32_e32 v62, v67, v68
	v_add_f32_e32 v38, v38, v61
	v_fmac_f32_e32 v71, v128, v128
	v_fmac_f32_e32 v72, v130, v130
	v_add_f32_e32 v63, v69, v70
	v_add_f32_e32 v38, v38, v62
	v_add_f32_e32 v38, v38, v63
	v_add_f32_e32 v58, v71, v72
	v_add_f32_e32 v38, v38, v58
	ds_bpermute_b32 v58, v3, v38
	s_waitcnt lgkmcnt(0)
	v_add_f32_e32 v38, v38, v58
	ds_bpermute_b32 v58, v52, v38
	s_waitcnt lgkmcnt(0)
	v_add_f32_e32 v38, v38, v58
	ds_bpermute_b32 v58, v53, v38
	s_waitcnt lgkmcnt(0)
	v_add_f32_e32 v38, v38, v58
	ds_bpermute_b32 v58, v54, v38
	s_waitcnt lgkmcnt(0)
	v_add_f32_e32 v38, v38, v58
	ds_bpermute_b32 v58, v55, v38
	s_waitcnt lgkmcnt(0)
	v_add_f32_e32 v38, v38, v58
	ds_bpermute_b32 v58, v56, v38
	s_waitcnt lgkmcnt(0)
	v_add_f32_e32 v38, v38, v58
	v_fmamk_f32 v38, v38, 0x3a000000, v57
	v_rsq_f32_e32 v38, v38
	s_and_saveexec_b64 s[14:15], vcc
	v_rcp_f32_e32 v58, v38
	global_store_dword v39, v58, s[0:1]
	s_or_b64 exec, exec, s[14:15]
	v_pk_mul_f32 v[156:157], v[156:157], v[38:39] op_sel_hi:[1,0]
	v_pk_mul_f32 v[158:159], v[158:159], v[38:39] op_sel_hi:[1,0]
	v_pk_mul_f32 v[152:153], v[152:153], v[38:39] op_sel_hi:[1,0]
	v_pk_mul_f32 v[154:155], v[154:155], v[38:39] op_sel_hi:[1,0]
	v_pk_mul_f32 v[148:149], v[148:149], v[38:39] op_sel_hi:[1,0]
	v_pk_mul_f32 v[150:151], v[150:151], v[38:39] op_sel_hi:[1,0]
	v_pk_mul_f32 v[144:145], v[144:145], v[38:39] op_sel_hi:[1,0]
	v_pk_mul_f32 v[146:147], v[146:147], v[38:39] op_sel_hi:[1,0]
	v_pk_mul_f32 v[140:141], v[140:141], v[38:39] op_sel_hi:[1,0]
	v_pk_mul_f32 v[142:143], v[142:143], v[38:39] op_sel_hi:[1,0]
	v_pk_mul_f32 v[136:137], v[136:137], v[38:39] op_sel_hi:[1,0]
	v_pk_mul_f32 v[138:139], v[138:139], v[38:39] op_sel_hi:[1,0]
	v_pk_mul_f32 v[132:133], v[132:133], v[38:39] op_sel_hi:[1,0]
	v_pk_mul_f32 v[134:135], v[134:135], v[38:39] op_sel_hi:[1,0]
	v_pk_mul_f32 v[128:129], v[128:129], v[38:39] op_sel_hi:[1,0]
	v_pk_mul_f32 v[130:131], v[130:131], v[38:39] op_sel_hi:[1,0]
	s_add_i32 s7, s7, s88
	s_add_u32 s0, s0, s2
	s_addc_u32 s1, s1, s3
	v_lshl_add_u64 v[50:51], v[50:51], 0, s[8:9]
	s_cmpk_gt_i32 s7, 0x7fff
	v_pk_mul_f32 v[156:157], v[156:157], v[80:81]
	v_pk_mul_f32 v[158:159], v[158:159], v[82:83]
	v_cvt_pk_bf16_f32 v156, v156, v157
	v_cvt_pk_bf16_f32 v157, v158, v159
	global_store_dwordx2 v[36:37], v[156:157], off offset:-2048
	v_pk_mul_f32 v[152:153], v[152:153], v[84:85]
	v_pk_mul_f32 v[154:155], v[154:155], v[86:87]
	v_cvt_pk_bf16_f32 v152, v152, v153
	v_cvt_pk_bf16_f32 v153, v154, v155
	global_store_dwordx2 v[36:37], v[152:153], off offset:-1536
	v_pk_mul_f32 v[148:149], v[148:149], v[88:89]
	v_pk_mul_f32 v[150:151], v[150:151], v[90:91]
	v_cvt_pk_bf16_f32 v148, v148, v149
	v_cvt_pk_bf16_f32 v149, v150, v151
	global_store_dwordx2 v[36:37], v[148:149], off offset:-1024
	v_pk_mul_f32 v[144:145], v[144:145], v[92:93]
	v_pk_mul_f32 v[146:147], v[146:147], v[94:95]
	v_cvt_pk_bf16_f32 v144, v144, v145
	v_cvt_pk_bf16_f32 v145, v146, v147
	global_store_dwordx2 v[36:37], v[144:145], off offset:-512
	v_pk_mul_f32 v[140:141], v[140:141], v[96:97]
	v_pk_mul_f32 v[142:143], v[142:143], v[98:99]
	v_cvt_pk_bf16_f32 v140, v140, v141
	v_cvt_pk_bf16_f32 v141, v142, v143
	global_store_dwordx2 v[36:37], v[140:141], off
	v_pk_mul_f32 v[136:137], v[136:137], v[100:101]
	v_pk_mul_f32 v[138:139], v[138:139], v[102:103]
	v_cvt_pk_bf16_f32 v136, v136, v137
	v_cvt_pk_bf16_f32 v137, v138, v139
	global_store_dwordx2 v[36:37], v[136:137], off offset:512
	v_pk_mul_f32 v[132:133], v[132:133], v[104:105]
	v_pk_mul_f32 v[134:135], v[134:135], v[106:107]
	v_cvt_pk_bf16_f32 v132, v132, v133
	v_cvt_pk_bf16_f32 v133, v134, v135
	global_store_dwordx2 v[36:37], v[132:133], off offset:1024
	v_pk_mul_f32 v[128:129], v[128:129], v[108:109]
	v_pk_mul_f32 v[130:131], v[130:131], v[110:111]
	v_cvt_pk_bf16_f32 v128, v128, v129
	v_cvt_pk_bf16_f32 v129, v130, v131
	global_store_dwordx2 v[36:37], v[128:129], off offset:1536
	v_lshl_add_u64 v[36:37], v[36:37], 0, s[10:11]
	s_cbranch_scc1 .LBB0_116
.LBB0_114:
	s_add_i32 s98, s7, s88
	s_cmpk_gt_i32 s98, 0x7fff
	s_cbranch_scc1 .Lp0n_nopfA
	v_lshl_add_u64 v[160:161], v[50:51], 0, s[8:9]
	global_load_dwordx4 v[156:159], v[160:161], off offset:-4096
	global_load_dwordx4 v[152:155], v[160:161], off offset:-3072
	global_load_dwordx4 v[148:151], v[160:161], off offset:-2048
	global_load_dwordx4 v[144:147], v[160:161], off offset:-1024
	global_load_dwordx4 v[140:143], v[160:161], off
	global_load_dwordx4 v[136:139], v[160:161], off offset:1024
	global_load_dwordx4 v[132:135], v[160:161], off offset:2048
	global_load_dwordx4 v[128:131], v[160:161], off offset:3072
	s_waitcnt vmcnt(17)
	s_branch .Lp0n_goA

; DI float frsq(float x) { return __builtin_amdgcn_rsqf(x); }
; DI void norm_row_bf16(const float* xrow, const float* g, bf16_t* orow, int lane, float* xs_out = nullptr) {
;     const f32x4* xr = (const f32x4*)xrow + lane; f32x4 v[8]; float s = 0.f;
; #pragma unroll
;     for (int j = 0; j < 8; ++j) { v[j] = xr[64 * j]; s += (v[j].x * v[j].x + v[j].y * v[j].y) + (v[j].z * v[j].z + v[j].w * v[j].w); }
;     s = wave_sum(s);
;     const float rs = frsq(s * (1.0f / DM) + 1e-6f);
.Lp0n_goA:
	v_mul_f32_e32 v38, v33, v33
	v_mul_f32_e32 v58, v35, v35
	v_mul_f32_e32 v59, v29, v29
	v_mul_f32_e32 v60, v31, v31
	v_mul_f32_e32 v61, v25, v25
	v_mul_f32_e32 v62, v27, v27
	v_fmac_f32_e32 v38, v32, v32
	v_fmac_f32_e32 v58, v34, v34
	v_fmac_f32_e32 v59, v28, v28
	v_fmac_f32_e32 v60, v30, v30
	v_mul_f32_e32 v63, v21, v21
	v_mul_f32_e32 v64, v23, v23
	v_fmac_f32_e32 v61, v24, v24
	v_fmac_f32_e32 v62, v26, v26
	v_add_f32_e32 v38, v38, v58
	v_add_f32_e32 v58, v59, v60
	v_mul_f32_e32 v65, v17, v17
	v_mul_f32_e32 v66, v19, v19
	v_fmac_f32_e32 v63, v20, v20
	v_fmac_f32_e32 v64, v22, v22
	v_add_f32_e32 v59, v61, v62
	v_add_f32_e32 v38, v38, v58
	v_mul_f32_e32 v67, v13, v13
	v_mul_f32_e32 v68, v15, v15
	v_fmac_f32_e32 v65, v16, v16
	v_fmac_f32_e32 v66, v18, v18
	v_add_f32_e32 v60, v63, v64
	v_add_f32_e32 v38, v38, v59
	v_mul_f32_e32 v69, v9, v9
	v_mul_f32_e32 v70, v11, v11
	v_fmac_f32_e32 v67, v12, v12
	v_fmac_f32_e32 v68, v14, v14
	v_add_f32_e32 v61, v65, v66
	v_add_f32_e32 v38, v38, v60
	v_mul_f32_e32 v71, v5, v5
	v_mul_f32_e32 v72, v7, v7
	v_fmac_f32_e32 v69, v8, v8
	v_fmac_f32_e32 v70, v10, v10
	v_add_f32_e32 v62, v67, v68
	v_add_f32_e32 v38, v38, v61
	v_fmac_f32_e32 v71, v4, v4
	v_fmac_f32_e32 v72, v6, v6
	v_add_f32_e32 v63, v69, v70
	v_add_f32_e32 v38, v38, v62
	v_add_f32_e32 v38, v38, v63
	v_add_f32_e32 v58, v71, v72
	v_add_f32_e32 v38, v38, v58
	ds_bpermute_b32 v58, v3, v38
	s_waitcnt lgkmcnt(0)
	v_add_f32_e32 v38, v38, v58
	ds_bpermute_b32 v58, v52, v38
	s_waitcnt lgkmcnt(0)
	v_add_f32_e32 v38, v38, v58
	ds_bpermute_b32 v58, v53, v38
	s_waitcnt lgkmcnt(0)
	v_add_f32_e32 v38, v38, v58
	ds_bpermute_b32 v58, v54, v38
	s_waitcnt lgkmcnt(0)
	v_add_f32_e32 v38, v38, v58
	ds_bpermute_b32 v58, v55, v38
	s_waitcnt lgkmcnt(0)
	v_add_f32_e32 v38, v38, v58
	ds_bpermute_b32 v58, v56, v38
	s_waitcnt lgkmcnt(0)
	v_add_f32_e32 v38, v38, v58
	v_fmamk_f32 v38, v38, 0x3a000000, v57
	v_rsq_f32_e32 v38, v38
	s_and_saveexec_b64 s[14:15], vcc
	s_cbranch_execz .LBB0_113
	v_rcp_f32_e32 v58, v38
	global_store_dword v39, v58, s[0:1]
	s_branch .LBB0_113
